# phase-2 prompt attention items dealt in reverse order (short items last)
# speedup vs baseline: 1.0192x; 1.0018x over previous
.LBB0_670:
	s_mov_b32 s5, s0
	s_add_i32 s0, s0, s92
	s_and_b32 s0, s0, 7
	s_lshl_b32 s1, s0, 8
	v_readlane_b32 s2, v251, 50
	s_add_u32 s2, s2, s1
	v_readlane_b32 s1, v251, 51
	s_addc_u32 s3, s1, 0
	v_writelane_b32 v250, s2, 10
	s_mul_i32 s1, s0, 0x208
	s_addk_i32 s1, 0x1040
	v_writelane_b32 v250, s3, 11
	v_writelane_b32 v250, s1, 12
	s_lshl_b32 s1, s0, 9
	s_add_i32 s1, s1, 0x207
	s_lshl_b32 s0, s0, 3
	v_writelane_b32 v250, s1, 13
	s_bitset1_b32 s0, 12
	v_writelane_b32 v250, s0, 14
	s_cmp_eq_u32 s5, 0
	s_cbranch_scc1 .Ldq_issue
	s_cmp_eq_u32 s5, 1
	s_cbranch_scc0 .Ldq_have_snap
	v_mbcnt_lo_u32_b32 v239, -1, 0
	v_mbcnt_hi_u32_b32 v239, -1, v239
	v_lshlrev_b32_e32 v239, 8, v239
	v_readlane_b32 s0, v251, 50
	v_readlane_b32 s1, v251, 51
	s_mov_b64 s[10:11], exec
	s_mov_b64 exec, 0xff
	s_nop 4
	global_load_dword v239, v239, s[0:1] sc1
	s_mov_b64 exec, s[10:11]
	s_waitcnt vmcnt(0)

.LBB0_681:
	s_andn2_b64 vcc, exec, s[0:1]
	s_cbranch_vccnz .LBB0_686
	s_cmp_gt_u32 s3, 15
	s_mov_b64 s[0:1], -1
	s_cbranch_scc0 .LBB0_684
	v_readlane_b32 s0, v250, 13
	s_sub_i32 s18, s0, s2
	s_mov_b64 s[0:1], 0
